# grid barrier: the flag poll loop re-polls at once (no s_sleep between polls)
# speedup vs baseline: 1.0123x; 1.0123x over previous
.Lgb2_spin:
	global_load_dword v2, v0, s[6:7] sc1
	s_waitcnt vmcnt(0)
	v_readfirstlane_b32 s15, v2
	s_cmp_ge_u32 s15, s14
	s_cbranch_scc1 .Lgb2_done
	s_add_i32 s11, s11, 1
	s_cmp_lt_u32 s11, 0x400000
	s_cbranch_scc1 .Lgb2_spin
